# v36 + VALU re-spacing (7.5): cross-half row-max exchange moved from after the last PV MFMA to the gap before it
# baseline (speedup 1.0000x reference)
; #define LAS __attribute__((address_space(3)))
; #define MFMA32(a, b, c) __builtin_amdgcn_mfma_f32_32x32x16_bf16((a), (b), (c), 0, 0, 0)
; DI int perm32k(int i) { return (i & 0x13) | ((i & 8) >> 1) | ((i & 4) << 1); }
; DI bf16x8 pack8(const f32x16& x, int s) { u32x4 p; p.x = pk2(x[8 * s], x[8 * s + 1]); p.y = pk2(x[8 * s + 2], x[8 * s + 3]); p.z = pk2(x[8 * s + 4], x[8 * s + 5]); p.w = pk2(x[8 * s + 6], x[8 * s + 7]); return __builtin_bit_cast(bf16x8, p); }
; DI void attn_unit(LAS unsigned char* lds, const bf16_t* __restrict__ Q, const bf16_t* __restrict__ Kg, const bf16_t* __restrict__ VT, bf16_t* __restrict__ MIX, int b, int h, int c0, int nq, int desc) {
;     ...
;       float mx = fmaxf(s0[0], s1[0]);
; #pragma unroll
;       for (int i = 1; i < 16; ++i) mx = fmaxf(mx, fmaxf(s0[i], s1[i]));
;       mx = fmaxf(mx, __shfl_xor(mx, 32));
;       const float mn = fmaxf(mrun, mx);
;       if (__builtin_amdgcn_ballot_w64(mn > mrun) != 0ull) {
;         const float alpha = __builtin_amdgcn_exp2f(mrun - mn); mrun = mn; lrun *= alpha;
; #pragma unroll
;         for (int d = 0; d < 4; ++d) O[d] = O[d] * alpha; }
; #pragma unroll
;       for (int i = 0; i < 16; ++i) { n0[i] = 0.f; n1[i] = 0.f; }
;       const LAS unsigned char* kb2 = lds + (buf ^ 1) * ATT_KB + perm32k(r31) * KROWB + 16 * hh;
;       __builtin_amdgcn_sched_barrier(0);
; #pragma unroll
;       for (int sx = 0; sx < 12; ++sx) { const bf16x8 a0 = *(const LAS bf16x8*)(kb2 + 32 * sx); const bf16x8 a1 = *(const LAS bf16x8*)(kb2 + 32 * KROWB + 32 * sx);
;         n0 = MFMA32(a0, qf[sx], n0); n1 = MFMA32(a1, qf[sx], n1);
; #pragma unroll
;         for (int j = 0; j < 3; ++j) { const int ei = 3 * sx + j; if (ei < 16) s0[ei] = __builtin_amdgcn_exp2f(s0[ei] - mrun); else if (ei < 32) s1[ei - 16] = __builtin_amdgcn_exp2f(s1[ei - 16] - mrun); }
;         __builtin_amdgcn_sched_barrier(0); }
;       float ps = 0.f;
; #pragma unroll
;       for (int i = 0; i < 16; ++i) ps += s0[i] + s1[i];
;       lrun += ps;
;       bf16x8 pf[4]; pf[0] = pack8(s0, 0); pf[1] = pack8(s0, 1); pf[2] = pack8(s1, 0); pf[3] = pack8(s1, 1);
;       const LAS unsigned char* vb = lds + 2 * ATT_KB + buf * ATT_VB + r31 * HROW + 16 * hh;
; #pragma unroll
;       for (int kk = 0; kk < 4; ++kk)
; #pragma unroll
;         for (int d = 0; d < 4; ++d) { const bf16x8 a = *(const LAS bf16x8*)(vb + d * 32 * HROW + 32 * kk); O[d] = MFMA32(a, pf[kk], O[d]); }
.Lnv_LBB0_551:
	s_waitcnt lgkmcnt(3)
	v_mfma_f32_32x32x16_bf16 v[50:65], v[212:215], v[74:77], v[50:65]
	v_max3_f32 v239, v239, v124, v125
	v_max3_f32 v241, v241, v126, v127
	v_mov_b64_e32 v[66:67], v[114:115]
	v_mov_b64_e32 v[68:69], v[116:117]
	s_waitcnt lgkmcnt(2)
	v_mfma_f32_32x32x16_bf16 v[34:49], v[218:221], v[74:77], v[34:49]
	v_max3_f32 v239, v239, v128, v129
	v_max_f32_e32 v241, v239, v241
	s_waitcnt lgkmcnt(1)
	v_mfma_f32_32x32x16_bf16 v[18:33], v[230:233], v[74:77], v[18:33]
	v_mov_b32_e32 v239, v241
	s_nop 1
	v_permlane32_swap_b32_e32 v241, v239
	v_max_f32_e32 v241, v241, v239
	s_waitcnt lgkmcnt(0)
	v_mfma_f32_32x32x16_bf16 v[2:17], v[234:237], v[74:77], v[2:17]
	v_mov_b64_e32 v[74:75], v[122:123]
	v_mov_b64_e32 v[76:77], v[124:125]
	s_add_i32 s99, s23, 131073
	s_or_b64 exec, exec, s[30:31]
	s_branch .LBB0_554
	s_andn2_b64 vcc, exec, s[26:27]
	s_cbranch_vccz .LBB0_560

; #define LAS __attribute__((address_space(3)))
; #define MFMA32(a, b, c) __builtin_amdgcn_mfma_f32_32x32x16_bf16((a), (b), (c), 0, 0, 0)
; DI int perm32k(int i) { return (i & 0x13) | ((i & 8) >> 1) | ((i & 4) << 1); }
; DI bf16x8 pack8(const f32x16& x, int s) { u32x4 p; p.x = pk2(x[8 * s], x[8 * s + 1]); p.y = pk2(x[8 * s + 2], x[8 * s + 3]); p.z = pk2(x[8 * s + 4], x[8 * s + 5]); p.w = pk2(x[8 * s + 6], x[8 * s + 7]); return __builtin_bit_cast(bf16x8, p); }
; DI void attn_unit(LAS unsigned char* lds, const bf16_t* __restrict__ Q, const bf16_t* __restrict__ Kg, const bf16_t* __restrict__ VT, bf16_t* __restrict__ MIX, int b, int h, int c0, int nq, int desc) {
;     ...
;       float mx = fmaxf(s0[0], s1[0]);
; #pragma unroll
;       for (int i = 1; i < 16; ++i) mx = fmaxf(mx, fmaxf(s0[i], s1[i]));
;       mx = fmaxf(mx, __shfl_xor(mx, 32));
;       const float mn = fmaxf(mrun, mx);
;       if (__builtin_amdgcn_ballot_w64(mn > mrun) != 0ull) {
;         const float alpha = __builtin_amdgcn_exp2f(mrun - mn); mrun = mn; lrun *= alpha;
; #pragma unroll
;         for (int d = 0; d < 4; ++d) O[d] = O[d] * alpha; }
; #pragma unroll
;       for (int i = 0; i < 16; ++i) { n0[i] = 0.f; n1[i] = 0.f; }
;       const LAS unsigned char* kb2 = lds + (buf ^ 1) * ATT_KB + perm32k(r31) * KROWB + 16 * hh;
;       __builtin_amdgcn_sched_barrier(0);
; #pragma unroll
;       for (int sx = 0; sx < 12; ++sx) { const bf16x8 a0 = *(const LAS bf16x8*)(kb2 + 32 * sx); const bf16x8 a1 = *(const LAS bf16x8*)(kb2 + 32 * KROWB + 32 * sx);
;         n0 = MFMA32(a0, qf[sx], n0); n1 = MFMA32(a1, qf[sx], n1);
; #pragma unroll
;         for (int j = 0; j < 3; ++j) { const int ei = 3 * sx + j; if (ei < 16) s0[ei] = __builtin_amdgcn_exp2f(s0[ei] - mrun); else if (ei < 32) s1[ei - 16] = __builtin_amdgcn_exp2f(s1[ei - 16] - mrun); }
;         __builtin_amdgcn_sched_barrier(0); }
;       float ps = 0.f;
; #pragma unroll
;       for (int i = 0; i < 16; ++i) ps += s0[i] + s1[i];
;       lrun += ps;
;       bf16x8 pf[4]; pf[0] = pack8(s0, 0); pf[1] = pack8(s0, 1); pf[2] = pack8(s1, 0); pf[3] = pack8(s1, 1);
;       const LAS unsigned char* vb = lds + 2 * ATT_KB + buf * ATT_VB + r31 * HROW + 16 * hh;
; #pragma unroll
;       for (int kk = 0; kk < 4; ++kk)
; #pragma unroll
;         for (int d = 0; d < 4; ++d) { const bf16x8 a = *(const LAS bf16x8*)(vb + d * 32 * HROW + 32 * kk); O[d] = MFMA32(a, pf[kk], O[d]); }
.Lnok_LBB0_583:
	s_waitcnt lgkmcnt(3)
	v_mfma_f32_32x32x16_bf16 v[16:31], v[236:239], v[112:115], v[16:31]
	ds_read_b128 v[236:239], v95 offset:65056
	v_add_f32_e32 v14, v14, v15
	v_add_f32_e32 v240, v240, v241
	v_mov_b64_e32 v[116:117], v[132:133]
	v_mov_b64_e32 v[124:125], v[140:141]
	s_waitcnt lgkmcnt(3)
	v_mfma_f32_32x32x16_bf16 v[64:79], v[2:5], v[120:123], v[64:79]
	ds_read_b128 v[2:5], v95 offset:51264
	v_add_f32_e32 v0, v14, v240
	v_mov_b64_e32 v[100:101], v[148:149]
	v_mov_b64_e32 v[108:109], v[156:157]
	s_waitcnt lgkmcnt(3)
	v_mfma_f32_32x32x16_bf16 v[48:63], v[6:9], v[120:123], v[48:63]
	ds_read_b128 v[6:9], v95 offset:55872
	v_add_f32_e32 v80, v80, v0
	v_mov_b64_e32 v[118:119], v[134:135]
	v_mov_b64_e32 v[126:127], v[142:143]
	s_waitcnt lgkmcnt(3)
	v_mfma_f32_32x32x16_bf16 v[32:47], v[10:13], v[120:123], v[32:47]
	ds_read_b128 v[10:13], v95 offset:60480
	s_xor_b32 s98, s71, 1
	s_mulk_i32 s98, 0x4800
	v_add_u32_e32 v235, s98, v230
	s_waitcnt vmcnt(0)
	ds_write_b128 v235, v[160:163] offset:51200
	ds_write_b128 v235, v[164:167] offset:51264
	v_max3_f32 v15, v128, v129, v130
	v_max3_f32 v241, v131, v132, v133
	s_waitcnt lgkmcnt(3)
	v_mfma_f32_32x32x16_bf16 v[16:31], v[236:239], v[120:123], v[16:31]
	ds_read_b128 v[236:239], v95 offset:65088
	v_max3_f32 v15, v15, v134, v135
	v_max3_f32 v241, v241, v136, v137
	v_mov_b64_e32 v[102:103], v[150:151]
	v_mov_b64_e32 v[110:111], v[158:159]
	s_waitcnt lgkmcnt(3)
	v_mfma_f32_32x32x16_bf16 v[64:79], v[2:5], v[96:99], v[64:79]
	ds_read_b128 v[2:5], v95 offset:51296
	v_max3_f32 v15, v15, v138, v139
	v_max3_f32 v241, v241, v140, v141
	v_mov_b64_e32 v[112:113], v[128:129]
	v_mov_b64_e32 v[114:115], v[130:131]
	s_waitcnt lgkmcnt(3)
	v_mfma_f32_32x32x16_bf16 v[48:63], v[6:9], v[96:99], v[48:63]
	ds_read_b128 v[6:9], v95 offset:55904
	v_max3_f32 v15, v15, v142, v143
	v_max3_f32 v241, v241, v144, v145
	v_mov_b64_e32 v[120:121], v[136:137]
	v_mov_b64_e32 v[122:123], v[138:139]
	s_waitcnt lgkmcnt(3)
	v_mfma_f32_32x32x16_bf16 v[32:47], v[10:13], v[96:99], v[32:47]
	ds_read_b128 v[10:13], v95 offset:60512
	v_max3_f32 v15, v15, v146, v147
	v_max3_f32 v241, v241, v148, v149
	s_waitcnt lgkmcnt(3)
	v_mfma_f32_32x32x16_bf16 v[16:31], v[236:239], v[96:99], v[16:31]
	ds_read_b128 v[236:239], v95 offset:65120
	v_max3_f32 v15, v15, v150, v151
	v_max3_f32 v241, v241, v152, v153
	s_waitcnt lgkmcnt(3)
	v_mfma_f32_32x32x16_bf16 v[64:79], v[2:5], v[104:107], v[64:79]
	v_max3_f32 v15, v15, v154, v155
	v_max3_f32 v241, v241, v156, v157
	v_mov_b64_e32 v[96:97], v[144:145]
	v_mov_b64_e32 v[98:99], v[146:147]
	s_waitcnt lgkmcnt(2)
	v_mfma_f32_32x32x16_bf16 v[48:63], v[6:9], v[104:107], v[48:63]
	v_max3_f32 v15, v15, v158, v159
	v_max_f32_e32 v241, v15, v241
	s_waitcnt lgkmcnt(1)
	v_mfma_f32_32x32x16_bf16 v[32:47], v[10:13], v[104:107], v[32:47]
	v_mov_b32_e32 v15, v241
	s_nop 1
	v_permlane32_swap_b32_e32 v241, v15
	v_max_f32_e32 v241, v241, v15
	s_waitcnt lgkmcnt(0)
	v_mfma_f32_32x32x16_bf16 v[16:31], v[236:239], v[104:107], v[16:31]
	v_mov_b64_e32 v[104:105], v[152:153]
	v_mov_b64_e32 v[106:107], v[154:155]
	s_add_i32 s99, s70, 65537
	s_add_i32 s99, s70, 65537
	s_or_b64 exec, exec, s[6:7]
	s_branch .LBB0_586
	s_andn2_b64 vcc, exec, s[26:27]
	s_cbranch_vccz .LBB0_592

; #define LAS __attribute__((address_space(3)))
; #define MFMA32(a, b, c) __builtin_amdgcn_mfma_f32_32x32x16_bf16((a), (b), (c), 0, 0, 0)
; DI int perm32k(int i) { return (i & 0x13) | ((i & 8) >> 1) | ((i & 4) << 1); }
; DI bf16x8 pack8(const f32x16& x, int s) { u32x4 p; p.x = pk2(x[8 * s], x[8 * s + 1]); p.y = pk2(x[8 * s + 2], x[8 * s + 3]); p.z = pk2(x[8 * s + 4], x[8 * s + 5]); p.w = pk2(x[8 * s + 6], x[8 * s + 7]); return __builtin_bit_cast(bf16x8, p); }
; DI void attn_unit(LAS unsigned char* lds, const bf16_t* __restrict__ Q, const bf16_t* __restrict__ Kg, const bf16_t* __restrict__ VT, bf16_t* __restrict__ MIX, int b, int h, int c0, int nq, int desc) {
;     ...
;       float mx = fmaxf(s0[0], s1[0]);
; #pragma unroll
;       for (int i = 1; i < 16; ++i) mx = fmaxf(mx, fmaxf(s0[i], s1[i]));
;       mx = fmaxf(mx, __shfl_xor(mx, 32));
;       const float mn = fmaxf(mrun, mx);
;       if (__builtin_amdgcn_ballot_w64(mn > mrun) != 0ull) {
;         const float alpha = __builtin_amdgcn_exp2f(mrun - mn); mrun = mn; lrun *= alpha;
; #pragma unroll
;         for (int d = 0; d < 4; ++d) O[d] = O[d] * alpha; }
; #pragma unroll
;       for (int i = 0; i < 16; ++i) { n0[i] = 0.f; n1[i] = 0.f; }
;       const LAS unsigned char* kb2 = lds + (buf ^ 1) * ATT_KB + perm32k(r31) * KROWB + 16 * hh;
;       __builtin_amdgcn_sched_barrier(0);
; #pragma unroll
;       for (int sx = 0; sx < 12; ++sx) { const bf16x8 a0 = *(const LAS bf16x8*)(kb2 + 32 * sx); const bf16x8 a1 = *(const LAS bf16x8*)(kb2 + 32 * KROWB + 32 * sx);
;         n0 = MFMA32(a0, qf[sx], n0); n1 = MFMA32(a1, qf[sx], n1);
; #pragma unroll
;         for (int j = 0; j < 3; ++j) { const int ei = 3 * sx + j; if (ei < 16) s0[ei] = __builtin_amdgcn_exp2f(s0[ei] - mrun); else if (ei < 32) s1[ei - 16] = __builtin_amdgcn_exp2f(s1[ei - 16] - mrun); }
;         __builtin_amdgcn_sched_barrier(0); }
;       float ps = 0.f;
; #pragma unroll
;       for (int i = 0; i < 16; ++i) ps += s0[i] + s1[i];
;       lrun += ps;
;       bf16x8 pf[4]; pf[0] = pack8(s0, 0); pf[1] = pack8(s0, 1); pf[2] = pack8(s1, 0); pf[3] = pack8(s1, 1);
;       const LAS unsigned char* vb = lds + 2 * ATT_KB + buf * ATT_VB + r31 * HROW + 16 * hh;
; #pragma unroll
;       for (int kk = 0; kk < 4; ++kk)
; #pragma unroll
;         for (int d = 0; d < 4; ++d) { const bf16x8 a = *(const LAS bf16x8*)(vb + d * 32 * HROW + 32 * kk); O[d] = MFMA32(a, pf[kk], O[d]); }
.Lnok_LBB0_2594:
	s_waitcnt lgkmcnt(3)
	v_mfma_f32_32x32x16_bf16 v[16:31], v[236:239], v[112:115], v[16:31]
	ds_read_b128 v[236:239], v95 offset:65056
	v_add_f32_e32 v14, v14, v15
	v_add_f32_e32 v240, v240, v241
	v_mov_b64_e32 v[116:117], v[132:133]
	v_mov_b64_e32 v[124:125], v[140:141]
	s_waitcnt lgkmcnt(3)
	v_mfma_f32_32x32x16_bf16 v[64:79], v[2:5], v[120:123], v[64:79]
	ds_read_b128 v[2:5], v95 offset:51264
	v_add_f32_e32 v0, v14, v240
	v_mov_b64_e32 v[100:101], v[148:149]
	v_mov_b64_e32 v[108:109], v[156:157]
	s_waitcnt lgkmcnt(3)
	v_mfma_f32_32x32x16_bf16 v[48:63], v[6:9], v[120:123], v[48:63]
	ds_read_b128 v[6:9], v95 offset:55872
	v_add_f32_e32 v80, v80, v0
	v_mov_b64_e32 v[118:119], v[134:135]
	v_mov_b64_e32 v[126:127], v[142:143]
	s_waitcnt lgkmcnt(3)
	v_mfma_f32_32x32x16_bf16 v[32:47], v[10:13], v[120:123], v[32:47]
	ds_read_b128 v[10:13], v95 offset:60480
	s_xor_b32 s98, s71, 1
	s_mulk_i32 s98, 0x4800
	v_add_u32_e32 v235, s98, v229
	s_waitcnt vmcnt(0)
	ds_write_b128 v235, v[160:163] offset:51200
	ds_write_b128 v235, v[164:167] offset:51264
	v_max3_f32 v15, v128, v129, v130
	v_max3_f32 v241, v131, v132, v133
	s_waitcnt lgkmcnt(3)
	v_mfma_f32_32x32x16_bf16 v[16:31], v[236:239], v[120:123], v[16:31]
	ds_read_b128 v[236:239], v95 offset:65088
	v_max3_f32 v15, v15, v134, v135
	v_max3_f32 v241, v241, v136, v137
	v_mov_b64_e32 v[102:103], v[150:151]
	v_mov_b64_e32 v[110:111], v[158:159]
	s_waitcnt lgkmcnt(3)
	v_mfma_f32_32x32x16_bf16 v[64:79], v[2:5], v[96:99], v[64:79]
	ds_read_b128 v[2:5], v95 offset:51296
	v_max3_f32 v15, v15, v138, v139
	v_max3_f32 v241, v241, v140, v141
	v_mov_b64_e32 v[112:113], v[128:129]
	v_mov_b64_e32 v[114:115], v[130:131]
	s_waitcnt lgkmcnt(3)
	v_mfma_f32_32x32x16_bf16 v[48:63], v[6:9], v[96:99], v[48:63]
	ds_read_b128 v[6:9], v95 offset:55904
	v_max3_f32 v15, v15, v142, v143
	v_max3_f32 v241, v241, v144, v145
	v_mov_b64_e32 v[120:121], v[136:137]
	v_mov_b64_e32 v[122:123], v[138:139]
	s_waitcnt lgkmcnt(3)
	v_mfma_f32_32x32x16_bf16 v[32:47], v[10:13], v[96:99], v[32:47]
	ds_read_b128 v[10:13], v95 offset:60512
	v_max3_f32 v15, v15, v146, v147
	v_max3_f32 v241, v241, v148, v149
	s_waitcnt lgkmcnt(3)
	v_mfma_f32_32x32x16_bf16 v[16:31], v[236:239], v[96:99], v[16:31]
	ds_read_b128 v[236:239], v95 offset:65120
	v_max3_f32 v15, v15, v150, v151
	v_max3_f32 v241, v241, v152, v153
	s_waitcnt lgkmcnt(3)
	v_mfma_f32_32x32x16_bf16 v[64:79], v[2:5], v[104:107], v[64:79]
	v_max3_f32 v15, v15, v154, v155
	v_max3_f32 v241, v241, v156, v157
	v_mov_b64_e32 v[96:97], v[144:145]
	v_mov_b64_e32 v[98:99], v[146:147]
	s_waitcnt lgkmcnt(2)
	v_mfma_f32_32x32x16_bf16 v[48:63], v[6:9], v[104:107], v[48:63]
	v_max3_f32 v15, v15, v158, v159
	v_max_f32_e32 v241, v15, v241
	s_waitcnt lgkmcnt(1)
	v_mfma_f32_32x32x16_bf16 v[32:47], v[10:13], v[104:107], v[32:47]
	v_mov_b32_e32 v15, v241
	s_nop 1
	v_permlane32_swap_b32_e32 v241, v15
	v_max_f32_e32 v241, v241, v15
	s_waitcnt lgkmcnt(0)
	v_mfma_f32_32x32x16_bf16 v[16:31], v[236:239], v[104:107], v[16:31]
	v_mov_b64_e32 v[104:105], v[152:153]
	v_mov_b64_e32 v[106:107], v[154:155]
	s_add_i32 s99, s70, 65537
	s_add_i32 s99, s70, 65537
	s_or_b64 exec, exec, s[6:7]
	s_branch .LBB0_2597
	s_andn2_b64 vcc, exec, s[26:27]
	s_cbranch_vccz .LBB0_2603
